# NSA softmax: masked logits use -inf so exp2 yields exact 0 and the per-element compare+select after each exp is dropped (A1, A2, selected-block stages)
# baseline (speedup 1.0000x reference)
; #define MFMA32(a, b, c) __builtin_amdgcn_mfma_f32_32x32x16_bf16((a), (b), (c), 0, 0, 0)
; DI float ex2(float x) { return __builtin_amdgcn_exp2f(x); }
; DI float red_max32(float x) { auto r = __builtin_amdgcn_permlane32_swap(__float_as_uint(x), __float_as_uint(x), false, false); return fmaxf(__uint_as_float(r[0]), __uint_as_float(r[1])); }
; DI void cmp_z(f32x16& s, int kt, int t, int t0, int hh, const float* tabh, float& mloc) {
;   const int nb = kt * 32;
;   if (t0 - (16 * (nb + 31) + 31) >= 127) {
;     const float bf = tabh[127];
; #pragma unroll
;     for (int i = 0; i < 16; ++i) { float z = fmaf(s[i], C1, bf); s[i] = z; mloc = fmaxf(mloc, z); }
;   } else {
; #pragma unroll
;     for (int i = 0; i < 16; ++i) {
;       int n = nb + (i & 7) + 8 * hh + 16 * (i >> 3);
;       int dc = t - (16 * n + 31); int dd = dc < 0 ? 0 : (dc > 127 ? 127 : dc);
;       float z = dc < 0 ? NEGB : fmaf(s[i], C1, tabh[dd]);
;       s[i] = z; mloc = fmaxf(mloc, z);
; DI void nsa_phase(unsigned char* lds, KParamPtr P, int wv) {
;     ...
;       for (int kt = 0; kt < nkt; ++kt) {
;         f32x16 s = zero16();
; #pragma unroll
;         for (int ks = 0; ks < 4; ++ks) s = MFMA32(kf[ks], qf[ks], s);
;         {
;           const int kn = kt + 1 < nkt ? kt + 1 : kt;
; #pragma unroll
;           for (int ks = 0; ks < 4; ++ks) kf[ks] = ldg8(kcb + kco + (unsigned)(kn * 32 * 64 + ks * 16));
;         }
;         float mloc = NEGB;
;         cmp_z(s, kt, t, t0, hh, tabh, mloc);
;         mloc = red_max32(mloc);
;         const float mn = fmaxf(m, mloc);
;         float ls = 0.f;
; #pragma unroll
;         for (int i = 0; i < 16; ++i) ls += (s[i] > -1e29f) ? ex2(s[i] - mn) : 0.f;
;         l = l * ex2(m - mn) + ls; m = mn;
;       }
.LBB0_943:
	s_or_b64 exec, exec, s[12:13]
	s_nop 5
	v_max_f32_e32 v2, v0, v0
	v_max_f32_e32 v3, v148, v148
	v_max_f32_e32 v2, v3, v2
	v_mov_b32_e32 v3, v2
	s_nop 1
	v_permlane32_swap_b32_e32 v2, v3
	v_max3_f32 v251, v146, v2, v3
	v_sub_f32_e32 v2, v42, v251
	v_exp_f32_e32 v2, v2
	v_sub_f32_e32 v3, v43, v251
	v_exp_f32_e32 v3, v3
	v_add_f32_e32 v2, 0, v2
	v_add_u32_e32 v48, 0xfffffe00, v48
	v_mov_b32_e32 v2, v2
	s_nop 1
	v_add_f32_e32 v2, v3, v2
	v_sub_f32_e32 v3, v44, v251
	v_exp_f32_e32 v3, v3
	s_nop 1
	v_add_f32_e32 v2, v3, v2
	v_sub_f32_e32 v3, v45, v251
	v_exp_f32_e32 v3, v3
	s_nop 1
	v_add_f32_e32 v2, v3, v2
	v_sub_f32_e32 v3, v38, v251
	v_exp_f32_e32 v3, v3
	s_nop 1
	v_add_f32_e32 v2, v3, v2
	v_sub_f32_e32 v3, v39, v251
	v_exp_f32_e32 v3, v3
	s_nop 1
	v_add_f32_e32 v2, v3, v2
	v_sub_f32_e32 v3, v36, v251
	v_exp_f32_e32 v3, v3
	s_nop 1
	v_add_f32_e32 v2, v3, v2
	v_sub_f32_e32 v3, v37, v251
	v_exp_f32_e32 v3, v3
	s_nop 1
	v_add_f32_e32 v2, v3, v2
	v_sub_f32_e32 v3, v34, v251
	v_exp_f32_e32 v3, v3
	s_nop 1
	v_add_f32_e32 v2, v3, v2
	v_sub_f32_e32 v3, v35, v251
	v_exp_f32_e32 v3, v3
	s_nop 1
	v_add_f32_e32 v2, v3, v2
	v_sub_f32_e32 v3, v46, v251
	v_exp_f32_e32 v3, v3
	s_nop 1
	v_add_f32_e32 v2, v3, v2
	v_sub_f32_e32 v3, v47, v251
	v_exp_f32_e32 v3, v3
	s_nop 1
	v_add_f32_e32 v2, v3, v2
	v_sub_f32_e32 v3, v40, v251
	v_exp_f32_e32 v3, v3
	s_nop 1
	v_add_f32_e32 v2, v3, v2
	v_sub_f32_e32 v3, v41, v251
	v_exp_f32_e32 v3, v3
	s_nop 1
	v_add_f32_e32 v2, v3, v2
	v_sub_f32_e32 v3, v147, v251
	v_exp_f32_e32 v3, v3
	s_nop 1
	v_sub_f32_e32 v0, v0, v251
	v_exp_f32_e32 v0, v0
	v_add_f32_e32 v2, v3, v2
	v_add_f32_e32 v0, v0, v2
	v_sub_f32_e32 v2, v146, v251
	v_exp_f32_e32 v2, v2
	v_cmp_eq_u32_e32 vcc, s17, v247
	s_or_b64 s[10:11], vcc, s[10:11]
	v_mov_b32_e32 v146, v251
	v_fmac_f32_e32 v0, v49, v2
	v_mov_b32_e32 v49, v0
	s_andn2_b64 exec, exec, s[10:11]
	s_cbranch_execz .LBB0_980
.LBB0_944:
	v_mov_b32_e32 v231, 0xff800000
	s_waitcnt vmcnt(0) lgkmcnt(0)
	v_mfma_f32_32x32x16_bf16 v[2:17], v[30:33], v[114:117], 0
	s_mov_b32 s2, s17
	s_add_i32 s17, s17, 1
	v_mov_b32_e32 v0, s2
	v_cmp_lt_i32_e32 vcc, s17, v247
	v_mov_b64_e32 v[152:153], v[28:29]
	v_mov_b64_e32 v[150:151], v[26:27]
	v_mfma_f32_32x32x16_bf16 v[2:17], v[18:21], v[118:121], v[2:17]
	v_mov_b32_e32 v18, s17
	v_cndmask_b32_e32 v0, v0, v18, vcc
	v_lshlrev_b32_e32 v0, 11, v0
	v_lshl_add_u64 v[26:27], v[0:1], 1, v[190:191]
	flat_load_dwordx4 v[30:33], v[26:27]
	flat_load_dwordx4 v[18:21], v[26:27] offset:32
	v_cmp_gt_i32_e32 vcc, s91, v48
	v_mfma_f32_32x32x16_bf16 v[2:17], v[22:25], v[122:125], v[2:17]
	flat_load_dwordx4 v[22:25], v[26:27] offset:64
	s_nop 0
	flat_load_dwordx4 v[26:29], v[26:27] offset:96
	v_mfma_f32_32x32x16_bf16 v[2:17], v[150:153], v[126:129], v[2:17]
	s_and_saveexec_b64 s[12:13], vcc
	s_xor_b64 s[12:13], exec, s[12:13]
	s_cbranch_execz .LBB0_978
	v_add_u32_e32 v148, v234, v48
	v_add_u32_e32 v0, 0x1f0, v148
	v_cmp_lt_i32_e32 vcc, -1, v0
	v_mov_b32_e32 v43, 0xff800000
	v_mov_b32_e32 v42, 0xff800000
	s_and_saveexec_b64 s[14:15], vcc
	s_cbranch_execz .LBB0_947
	v_min_u32_e32 v0, 0x7f, v0
	v_lshl_add_u32 v0, v0, 2, v250
	ds_read_b32 v42, v0
	s_waitcnt lgkmcnt(0)
	v_fmac_f32_e32 v42, 0x3e38aa3b, v2

; DI void cmp_z(f32x16& s, int kt, int t, int t0, int hh, const float* tabh, float& mloc) {
;     ...
;     for (int i = 0; i < 16; ++i) {
;       int n = nb + (i & 7) + 8 * hh + 16 * (i >> 3);
;       int dc = t - (16 * n + 31); int dd = dc < 0 ? 0 : (dc > 127 ? 127 : dc);
;       float z = dc < 0 ? NEGB : fmaf(s[i], C1, tabh[dd]);
;       s[i] = z; mloc = fmaxf(mloc, z);
.LBB0_949:
	s_or_b64 exec, exec, s[14:15]
	v_add_u32_e32 v0, 0x1d0, v148
	v_cmp_lt_i32_e32 vcc, -1, v0
	v_mov_b32_e32 v45, 0xff800000
	v_mov_b32_e32 v44, 0xff800000
	s_and_saveexec_b64 s[14:15], vcc
	s_cbranch_execz .LBB0_951
	v_min_u32_e32 v0, 0x7f, v0
	v_lshl_add_u32 v0, v0, 2, v250
	ds_read_b32 v44, v0
	s_waitcnt lgkmcnt(0)
	v_fmac_f32_e32 v44, 0x3e38aa3b, v4

; DI void cmp_z(f32x16& s, int kt, int t, int t0, int hh, const float* tabh, float& mloc) {
;     ...
;     for (int i = 0; i < 16; ++i) {
;       int n = nb + (i & 7) + 8 * hh + 16 * (i >> 3);
;       int dc = t - (16 * n + 31); int dd = dc < 0 ? 0 : (dc > 127 ? 127 : dc);
;       float z = dc < 0 ? NEGB : fmaf(s[i], C1, tabh[dd]);
;       s[i] = z; mloc = fmaxf(mloc, z);
.LBB0_953:
	s_or_b64 exec, exec, s[14:15]
	v_add_u32_e32 v0, 0x1b0, v148
	v_cmp_lt_i32_e32 vcc, -1, v0
	v_mov_b32_e32 v39, 0xff800000
	v_mov_b32_e32 v38, 0xff800000
	s_and_saveexec_b64 s[14:15], vcc
	s_cbranch_execz .LBB0_955
	v_min_u32_e32 v0, 0x7f, v0
	v_lshl_add_u32 v0, v0, 2, v250
	ds_read_b32 v38, v0
	s_waitcnt lgkmcnt(0)
	v_fmac_f32_e32 v38, 0x3e38aa3b, v6

; DI void cmp_z(f32x16& s, int kt, int t, int t0, int hh, const float* tabh, float& mloc) {
;     ...
;     for (int i = 0; i < 16; ++i) {
;       int n = nb + (i & 7) + 8 * hh + 16 * (i >> 3);
;       int dc = t - (16 * n + 31); int dd = dc < 0 ? 0 : (dc > 127 ? 127 : dc);
;       float z = dc < 0 ? NEGB : fmaf(s[i], C1, tabh[dd]);
;       s[i] = z; mloc = fmaxf(mloc, z);
.LBB0_957:
	s_or_b64 exec, exec, s[14:15]
	v_add_u32_e32 v0, 0x190, v148
	v_cmp_lt_i32_e32 vcc, -1, v0
	v_mov_b32_e32 v37, 0xff800000
	v_mov_b32_e32 v36, 0xff800000
	s_and_saveexec_b64 s[14:15], vcc
	s_cbranch_execz .LBB0_959
	v_min_u32_e32 v0, 0x7f, v0
	v_lshl_add_u32 v0, v0, 2, v250
	ds_read_b32 v36, v0
	s_waitcnt lgkmcnt(0)
	v_fmac_f32_e32 v36, 0x3e38aa3b, v8

; DI void cmp_z(f32x16& s, int kt, int t, int t0, int hh, const float* tabh, float& mloc) {
;     ...
;     for (int i = 0; i < 16; ++i) {
;       int n = nb + (i & 7) + 8 * hh + 16 * (i >> 3);
;       int dc = t - (16 * n + 31); int dd = dc < 0 ? 0 : (dc > 127 ? 127 : dc);
;       float z = dc < 0 ? NEGB : fmaf(s[i], C1, tabh[dd]);
;       s[i] = z; mloc = fmaxf(mloc, z);
.LBB0_961:
	s_or_b64 exec, exec, s[14:15]
	v_add_u32_e32 v0, 0xf0, v148
	v_cmp_lt_i32_e32 vcc, -1, v0
	v_mov_b32_e32 v35, 0xff800000
	v_mov_b32_e32 v34, 0xff800000
	s_and_saveexec_b64 s[14:15], vcc
	s_cbranch_execz .LBB0_963
	v_min_u32_e32 v0, 0x7f, v0
	v_lshl_add_u32 v0, v0, 2, v250
	ds_read_b32 v34, v0
	s_waitcnt lgkmcnt(0)
	v_fmac_f32_e32 v34, 0x3e38aa3b, v10

; DI void cmp_z(f32x16& s, int kt, int t, int t0, int hh, const float* tabh, float& mloc) {
;     ...
;     for (int i = 0; i < 16; ++i) {
;       int n = nb + (i & 7) + 8 * hh + 16 * (i >> 3);
;       int dc = t - (16 * n + 31); int dd = dc < 0 ? 0 : (dc > 127 ? 127 : dc);
;       float z = dc < 0 ? NEGB : fmaf(s[i], C1, tabh[dd]);
;       s[i] = z; mloc = fmaxf(mloc, z);
.LBB0_965:
	s_or_b64 exec, exec, s[14:15]
	v_add_u32_e32 v0, 0xd0, v148
	v_cmp_lt_i32_e32 vcc, -1, v0
	v_mov_b32_e32 v47, 0xff800000
	v_mov_b32_e32 v46, 0xff800000
	s_and_saveexec_b64 s[14:15], vcc
	s_cbranch_execz .LBB0_967
	v_min_u32_e32 v0, 0x7f, v0
	v_lshl_add_u32 v0, v0, 2, v250
	ds_read_b32 v46, v0
	s_waitcnt lgkmcnt(0)
	v_fmac_f32_e32 v46, 0x3e38aa3b, v12

; DI void cmp_z(f32x16& s, int kt, int t, int t0, int hh, const float* tabh, float& mloc) {
;     ...
;     for (int i = 0; i < 16; ++i) {
;       int n = nb + (i & 7) + 8 * hh + 16 * (i >> 3);
;       int dc = t - (16 * n + 31); int dd = dc < 0 ? 0 : (dc > 127 ? 127 : dc);
;       float z = dc < 0 ? NEGB : fmaf(s[i], C1, tabh[dd]);
;       s[i] = z; mloc = fmaxf(mloc, z);
.LBB0_969:
	s_or_b64 exec, exec, s[14:15]
	v_add_u32_e32 v0, 0xb0, v148
	v_cmp_lt_i32_e32 vcc, -1, v0
	v_mov_b32_e32 v41, 0xff800000
	v_mov_b32_e32 v40, 0xff800000
	s_and_saveexec_b64 s[14:15], vcc
	s_cbranch_execz .LBB0_971
	v_min_u32_e32 v0, 0x7f, v0
	v_lshl_add_u32 v0, v0, 2, v250
	ds_read_b32 v40, v0
	s_waitcnt lgkmcnt(0)
	v_fmac_f32_e32 v40, 0x3e38aa3b, v14

; DI void cmp_z(f32x16& s, int kt, int t, int t0, int hh, const float* tabh, float& mloc) {
;     ...
;     for (int i = 0; i < 16; ++i) {
;       int n = nb + (i & 7) + 8 * hh + 16 * (i >> 3);
;       int dc = t - (16 * n + 31); int dd = dc < 0 ? 0 : (dc > 127 ? 127 : dc);
;       float z = dc < 0 ? NEGB : fmaf(s[i], C1, tabh[dd]);
;       s[i] = z; mloc = fmaxf(mloc, z);
.LBB0_973:
	s_or_b64 exec, exec, s[14:15]
	v_add_u32_e32 v2, 0x90, v148
	v_cmp_lt_i32_e32 vcc, -1, v2
	v_mov_b32_e32 v0, 0xff800000
	v_mov_b32_e32 v147, 0xff800000
	s_and_saveexec_b64 s[14:15], vcc
	s_cbranch_execz .LBB0_975
	v_min_u32_e32 v2, 0x7f, v2
	v_lshl_add_u32 v2, v2, 2, v250
	ds_read_b32 v147, v2
	s_waitcnt lgkmcnt(0)
	v_fmac_f32_e32 v147, 0x3e38aa3b, v16

; #define MFMA32(a, b, c) __builtin_amdgcn_mfma_f32_32x32x16_bf16((a), (b), (c), 0, 0, 0)
; DI float ex2(float x) { return __builtin_amdgcn_exp2f(x); }
; #define SHXF(v, m) bperm_f(lane ^ (m), (v))
; DI void cmp_z(f32x16& s, int kt, int t, int t0, int hh, const float* tabh, float& mloc) {
;     ...
;     for (int i = 0; i < 16; ++i) {
;       int n = nb + (i & 7) + 8 * hh + 16 * (i >> 3);
;       int dc = t - (16 * n + 31); int dd = dc < 0 ? 0 : (dc > 127 ? 127 : dc);
;       float z = dc < 0 ? NEGB : fmaf(s[i], C1, tabh[dd]);
;       s[i] = z; mloc = fmaxf(mloc, z);
; DI void nsa_phase(unsigned char* lds, KParamPtr P, int wv) {
;     ...
;       for (int kt = 0; kt < nkt; ++kt) {
;         {
;           bf16x8 vf[4];
; #pragma unroll
;           for (int st = 0; st < 2; ++st)
; #pragma unroll
;             for (int et = 0; et < 2; ++et) vf[st * 2 + et] = ldg8(vcb + (unsigned)((et * 32 + l31) * 512 + kt * 32 + st * 16 + hh * 8));
;           f32x16 s = zero16();
; #pragma unroll
;           for (int ks = 0; ks < 4; ++ks) s = MFMA32(kf[ks], qf[ks], s);
;           {
;             const int kn = kt + 1 < nkt ? kt + 1 : kt;
; #pragma unroll
;             for (int ks = 0; ks < 4; ++ks) kf[ks] = ldg8(kcb + kco + (unsigned)(kn * 32 * 64 + ks * 16));
;           }
;           float mloc = NEGB;
;           cmp_z(s, kt, t, t0, hh, tabh, mloc);
; #pragma unroll
;           for (int i = 0; i < 16; ++i) s[i] = (s[i] > -1e29f) ? ex2(s[i] - m) * inv : 0.f;
;           const float G00 = s[0] + s[1] + s[2] + s[3], G01 = s[4] + s[5] + s[6] + s[7];
;           const float G10 = s[8] + s[9] + s[10] + s[11], G11 = s[12] + s[13] + s[14] + s[15];
;           const float pe0 = SHXF(s[7], 32), pe1 = SHXF(s[15], 32);
;           const float X0 = hh ? pe0 : carry;
;           const float X1 = hh ? pe1 : pe0;
;           float* sp = scw + (8 * kt + 2 * hh) * 32 + l31;
;           sp[0] += 2.f * G00 - s[3] + X0;
;           sp[32] += 2.f * G01 - s[7] + s[3];
;           sp[4 * 32] += 2.f * G10 - s[11] + X1;
;           sp[5 * 32] += 2.f * G11 - s[15] + s[11];
;           carry = pe1;
.LBB0_983:
	s_or_b64 exec, exec, s[12:13]
	s_nop 5
	v_sub_f32_e32 v34, v200, v251
	v_sub_f32_e32 v35, v201, v251
	v_exp_f32_e32 v34, v34
	v_exp_f32_e32 v35, v35
	v_sub_f32_e32 v36, v202, v251
	v_sub_f32_e32 v37, v203, v251
	v_exp_f32_e32 v36, v36
	v_exp_f32_e32 v37, v37
	v_pk_mul_f32 v[34:35], v[196:197], v[34:35]
	ds_read2_b32 v[38:39], v253 offset1:32
	v_lshl_add_u64 v[198:199], v[198:199], 0, 64
	v_mov_b32_e32 v40, v35
	v_add_u32_e32 v252, 0xfffffe00, v252
	s_nop 0
	v_mov_b32_e32 v41, v34
	v_pk_mul_f32 v[34:35], v[196:197], v[36:37]
	v_sub_f32_e32 v36, v204, v251
	v_sub_f32_e32 v37, v205, v251
	v_exp_f32_e32 v36, v36
	v_exp_f32_e32 v37, v37
	s_nop 1
	v_mov_b32_e32 v42, v35
	s_nop 1
	v_mov_b32_e32 v43, v34
	v_pk_mul_f32 v[34:35], v[196:197], v[36:37]
	v_sub_f32_e32 v36, v206, v251
	v_sub_f32_e32 v37, v207, v251
	v_exp_f32_e32 v36, v36
	v_exp_f32_e32 v37, v37
	s_nop 1
	v_mov_b32_e32 v44, v35
	s_nop 1
	v_mov_b32_e32 v45, v34
	v_pk_mul_f32 v[34:35], v[196:197], v[36:37]
	v_sub_f32_e32 v36, v208, v251
	v_sub_f32_e32 v37, v209, v251
	v_exp_f32_e32 v36, v36
	v_exp_f32_e32 v37, v37
	s_nop 1
	v_mov_b32_e32 v46, v35
	s_nop 1
	v_mov_b32_e32 v47, v34
	v_pk_mul_f32 v[34:35], v[196:197], v[36:37]
	v_sub_f32_e32 v36, v210, v251
	v_sub_f32_e32 v37, v211, v251
	v_exp_f32_e32 v36, v36
	v_exp_f32_e32 v37, v37
	ds_bpermute_b32 v209, v227, v46
	s_nop 0
	v_mov_b32_e32 v48, v35
	s_nop 1
	v_mov_b32_e32 v49, v34
	v_pk_mul_f32 v[34:35], v[196:197], v[36:37]
	v_sub_f32_e32 v36, v212, v251
	v_sub_f32_e32 v37, v213, v251
	v_exp_f32_e32 v36, v36
	v_exp_f32_e32 v37, v37
	s_nop 1
	v_mov_b32_e32 v200, v35
	s_nop 1
	v_mov_b32_e32 v201, v34
	v_pk_mul_f32 v[34:35], v[196:197], v[36:37]
	v_sub_f32_e32 v36, v221, v251
	v_sub_f32_e32 v37, v0, v251
	v_exp_f32_e32 v36, v36
	v_exp_f32_e32 v37, v37
	s_nop 1
	v_mov_b32_e32 v202, v35
	s_nop 1
	v_mov_b32_e32 v203, v34
	v_pk_mul_f32 v[34:35], v[196:197], v[36:37]
	v_cvt_pk_bf16_f32 v36, v45, v44
	v_cvt_pk_bf16_f32 v37, v47, v46
	v_mov_b32_e32 v0, v35
	v_cvt_pk_bf16_f32 v35, v43, v42
	ds_bpermute_b32 v210, v227, v0
	v_mov_b32_e32 v204, v34
	v_add_f32_e32 v34, v41, v40
	v_add_f32_e32 v34, v43, v34
	v_add_f32_e32 v205, v42, v34
	v_add_f32_e32 v34, v45, v44
	v_add_f32_e32 v34, v47, v34
	v_add_f32_e32 v206, v46, v34
	v_add_f32_e32 v34, v49, v48
	v_add_f32_e32 v34, v201, v34
	v_add_f32_e32 v207, v200, v34
	v_add_f32_e32 v34, v203, v202
	v_add_f32_e32 v34, v204, v34
	v_add_f32_e32 v208, v0, v34
	v_cvt_pk_bf16_f32 v34, v41, v40
	s_waitcnt lgkmcnt(0)
	v_cndmask_b32_e64 v40, v209, v219, s[4:5]
	v_fma_f32 v43, v205, 2.0, -v42
	s_waitcnt vmcnt(0)
	v_mfma_f32_32x32x16_bf16 v[18:33], v[158:161], v[34:37], v[18:33]
	v_add_f32_e32 v40, v40, v43
	v_add_f32_e32 v38, v38, v40
	v_fma_f32 v40, v206, 2.0, -v46
	v_add_f32_e32 v40, v42, v40
	v_cndmask_b32_e64 v41, v210, v209, s[4:5]
	v_cmp_eq_u32_e32 vcc, s17, v247
	s_or_b64 s[10:11], vcc, s[10:11]
	v_mfma_f32_32x32x16_bf16 v[2:17], v[150:153], v[34:37], v[2:17]
	v_add_f32_e32 v34, v39, v40
	ds_write2_b32 v253, v38, v34 offset1:32
	v_cvt_pk_bf16_f32 v34, v49, v48
	v_cvt_pk_bf16_f32 v35, v201, v200
	v_cvt_pk_bf16_f32 v36, v203, v202
	v_cvt_pk_bf16_f32 v37, v204, v0
	ds_read2_b32 v[38:39], v253 offset0:128 offset1:160
	v_fma_f32 v40, v207, 2.0, -v200
	v_mfma_f32_32x32x16_bf16 v[18:33], v[154:157], v[34:37], v[18:33]
	v_fma_f32 v0, v208, 2.0, -v0
	v_add_f32_e32 v40, v41, v40
	v_add_f32_e32 v0, v200, v0
	s_waitcnt lgkmcnt(0)
	v_add_f32_e32 v38, v38, v40
	v_add_f32_e32 v0, v39, v0
	ds_write2_b32 v253, v38, v0 offset0:128 offset1:160
	v_add_u32_e32 v253, 0x400, v253
	v_mfma_f32_32x32x16_bf16 v[2:17], v[146:149], v[34:37], v[2:17]
	v_mov_b32_e32 v219, v210
	s_andn2_b64 exec, exec, s[10:11]
	s_cbranch_execz .LBB0_939
.LBB0_984:
	v_mov_b32_e32 v231, 0xff800000
	s_mov_b32 s12, 0xffff7fe0
	v_add_co_u32_e32 v34, vcc, s12, v198
	s_movk_i32 s12, 0x8000
	s_nop 0
	v_addc_co_u32_e32 v35, vcc, -1, v199, vcc
	v_add_co_u32_e32 v36, vcc, s3, v198
	s_mov_b32 s2, s17
	s_nop 0
	v_addc_co_u32_e32 v37, vcc, -1, v199, vcc
	flat_load_dwordx4 v[158:161], v[34:35]
	flat_load_dwordx4 v[150:153], v[36:37]
	v_mfma_f32_32x32x16_bf16 v[34:49], v[130:133], v[114:117], 0
	v_add_co_u32_e32 v130, vcc, s12, v198
	s_add_i32 s17, s17, 1
	s_nop 0
	v_addc_co_u32_e32 v131, vcc, -1, v199, vcc
	flat_load_dwordx4 v[154:157], v[130:131]
	flat_load_dwordx4 v[146:149], v[198:199]
	v_mov_b32_e32 v0, s2
	v_mfma_f32_32x32x16_bf16 v[34:49], v[134:137], v[118:121], v[34:49]
	v_mov_b32_e32 v130, s17
	v_cmp_lt_i32_e32 vcc, s17, v247
	v_mov_b64_e32 v[202:203], v[144:145]
	v_mov_b64_e32 v[200:201], v[142:143]
	v_cndmask_b32_e32 v0, v0, v130, vcc
	v_lshlrev_b32_e32 v0, 11, v0
	v_lshl_add_u64 v[142:143], v[0:1], 1, v[190:191]
	flat_load_dwordx4 v[130:133], v[142:143]
	flat_load_dwordx4 v[134:137], v[142:143] offset:32
	v_mfma_f32_32x32x16_bf16 v[34:49], v[138:141], v[122:125], v[34:49]
	flat_load_dwordx4 v[138:141], v[142:143] offset:64
	s_nop 0
	flat_load_dwordx4 v[142:145], v[142:143] offset:96
	v_cmp_gt_i32_e32 vcc, s91, v252
	v_mfma_f32_32x32x16_bf16 v[34:49], v[200:203], v[126:129], v[34:49]
	s_and_saveexec_b64 s[12:13], vcc
	s_xor_b64 s[12:13], exec, s[12:13]
	s_cbranch_execz .LBB0_1018
	v_add_u32_e32 v231, v234, v252
	v_add_u32_e32 v0, 0x1f0, v231
	v_cmp_lt_i32_e32 vcc, -1, v0
	v_mov_b32_e32 v201, 0xff800000
	v_mov_b32_e32 v200, 0xff800000
	s_and_saveexec_b64 s[14:15], vcc
	s_cbranch_execz .LBB0_987
	v_min_u32_e32 v0, 0x7f, v0
	v_lshl_add_u32 v0, v0, 2, v250
	ds_read_b32 v200, v0
	s_waitcnt lgkmcnt(0)
	v_fmac_f32_e32 v200, 0x3e38aa3b, v34

; DI void cmp_z(f32x16& s, int kt, int t, int t0, int hh, const float* tabh, float& mloc) {
;     ...
;     for (int i = 0; i < 16; ++i) {
;       int n = nb + (i & 7) + 8 * hh + 16 * (i >> 3);
;       int dc = t - (16 * n + 31); int dd = dc < 0 ? 0 : (dc > 127 ? 127 : dc);
;       float z = dc < 0 ? NEGB : fmaf(s[i], C1, tabh[dd]);
;       s[i] = z; mloc = fmaxf(mloc, z);
.LBB0_989:
	s_or_b64 exec, exec, s[14:15]
	v_add_u32_e32 v0, 0x1d0, v231
	v_cmp_lt_i32_e32 vcc, -1, v0
	v_mov_b32_e32 v203, 0xff800000
	v_mov_b32_e32 v202, 0xff800000
	s_and_saveexec_b64 s[14:15], vcc
	s_cbranch_execz .LBB0_991
	v_min_u32_e32 v0, 0x7f, v0
	v_lshl_add_u32 v0, v0, 2, v250
	ds_read_b32 v202, v0
	s_waitcnt lgkmcnt(0)
	v_fmac_f32_e32 v202, 0x3e38aa3b, v36

; DI void cmp_z(f32x16& s, int kt, int t, int t0, int hh, const float* tabh, float& mloc) {
;     ...
;     for (int i = 0; i < 16; ++i) {
;       int n = nb + (i & 7) + 8 * hh + 16 * (i >> 3);
;       int dc = t - (16 * n + 31); int dd = dc < 0 ? 0 : (dc > 127 ? 127 : dc);
;       float z = dc < 0 ? NEGB : fmaf(s[i], C1, tabh[dd]);
;       s[i] = z; mloc = fmaxf(mloc, z);
.LBB0_993:
	s_or_b64 exec, exec, s[14:15]
	v_add_u32_e32 v0, 0x1b0, v231
	v_cmp_lt_i32_e32 vcc, -1, v0
	v_mov_b32_e32 v205, 0xff800000
	v_mov_b32_e32 v204, 0xff800000
	s_and_saveexec_b64 s[14:15], vcc
	s_cbranch_execz .LBB0_995
	v_min_u32_e32 v0, 0x7f, v0
	v_lshl_add_u32 v0, v0, 2, v250
	ds_read_b32 v204, v0
	s_waitcnt lgkmcnt(0)
	v_fmac_f32_e32 v204, 0x3e38aa3b, v38

; DI void cmp_z(f32x16& s, int kt, int t, int t0, int hh, const float* tabh, float& mloc) {
;     ...
;     for (int i = 0; i < 16; ++i) {
;       int n = nb + (i & 7) + 8 * hh + 16 * (i >> 3);
;       int dc = t - (16 * n + 31); int dd = dc < 0 ? 0 : (dc > 127 ? 127 : dc);
;       float z = dc < 0 ? NEGB : fmaf(s[i], C1, tabh[dd]);
;       s[i] = z; mloc = fmaxf(mloc, z);
.LBB0_997:
	s_or_b64 exec, exec, s[14:15]
	v_add_u32_e32 v0, 0x190, v231
	v_cmp_lt_i32_e32 vcc, -1, v0
	v_mov_b32_e32 v207, 0xff800000
	v_mov_b32_e32 v206, 0xff800000
	s_and_saveexec_b64 s[14:15], vcc
	s_cbranch_execz .LBB0_999
	v_min_u32_e32 v0, 0x7f, v0
	v_lshl_add_u32 v0, v0, 2, v250
	ds_read_b32 v206, v0
	s_waitcnt lgkmcnt(0)
	v_fmac_f32_e32 v206, 0x3e38aa3b, v40

; DI void cmp_z(f32x16& s, int kt, int t, int t0, int hh, const float* tabh, float& mloc) {
;     ...
;     for (int i = 0; i < 16; ++i) {
;       int n = nb + (i & 7) + 8 * hh + 16 * (i >> 3);
;       int dc = t - (16 * n + 31); int dd = dc < 0 ? 0 : (dc > 127 ? 127 : dc);
;       float z = dc < 0 ? NEGB : fmaf(s[i], C1, tabh[dd]);
;       s[i] = z; mloc = fmaxf(mloc, z);
.LBB0_1001:
	s_or_b64 exec, exec, s[14:15]
	v_add_u32_e32 v0, 0xf0, v231
	v_cmp_lt_i32_e32 vcc, -1, v0
	v_mov_b32_e32 v209, 0xff800000
	v_mov_b32_e32 v208, 0xff800000
	s_and_saveexec_b64 s[14:15], vcc
	s_cbranch_execz .LBB0_1003
	v_min_u32_e32 v0, 0x7f, v0
	v_lshl_add_u32 v0, v0, 2, v250
	ds_read_b32 v208, v0
	s_waitcnt lgkmcnt(0)
	v_fmac_f32_e32 v208, 0x3e38aa3b, v42

; DI void cmp_z(f32x16& s, int kt, int t, int t0, int hh, const float* tabh, float& mloc) {
;     ...
;     for (int i = 0; i < 16; ++i) {
;       int n = nb + (i & 7) + 8 * hh + 16 * (i >> 3);
;       int dc = t - (16 * n + 31); int dd = dc < 0 ? 0 : (dc > 127 ? 127 : dc);
;       float z = dc < 0 ? NEGB : fmaf(s[i], C1, tabh[dd]);
;       s[i] = z; mloc = fmaxf(mloc, z);
.LBB0_1005:
	s_or_b64 exec, exec, s[14:15]
	v_add_u32_e32 v0, 0xd0, v231
	v_cmp_lt_i32_e32 vcc, -1, v0
	v_mov_b32_e32 v211, 0xff800000
	v_mov_b32_e32 v210, 0xff800000
	s_and_saveexec_b64 s[14:15], vcc
	s_cbranch_execz .LBB0_1007
	v_min_u32_e32 v0, 0x7f, v0
	v_lshl_add_u32 v0, v0, 2, v250
	ds_read_b32 v210, v0
	s_waitcnt lgkmcnt(0)
	v_fmac_f32_e32 v210, 0x3e38aa3b, v44

; DI void cmp_z(f32x16& s, int kt, int t, int t0, int hh, const float* tabh, float& mloc) {
;     ...
;     for (int i = 0; i < 16; ++i) {
;       int n = nb + (i & 7) + 8 * hh + 16 * (i >> 3);
;       int dc = t - (16 * n + 31); int dd = dc < 0 ? 0 : (dc > 127 ? 127 : dc);
;       float z = dc < 0 ? NEGB : fmaf(s[i], C1, tabh[dd]);
;       s[i] = z; mloc = fmaxf(mloc, z);
.LBB0_1009:
	s_or_b64 exec, exec, s[14:15]
	v_add_u32_e32 v0, 0xb0, v231
	v_cmp_lt_i32_e32 vcc, -1, v0
	v_mov_b32_e32 v213, 0xff800000
	v_mov_b32_e32 v212, 0xff800000
	s_and_saveexec_b64 s[14:15], vcc
	s_cbranch_execz .LBB0_1011
	v_min_u32_e32 v0, 0x7f, v0
	v_lshl_add_u32 v0, v0, 2, v250
	ds_read_b32 v212, v0
	s_waitcnt lgkmcnt(0)
	v_fmac_f32_e32 v212, 0x3e38aa3b, v46

; DI void cmp_z(f32x16& s, int kt, int t, int t0, int hh, const float* tabh, float& mloc) {
;     ...
;     for (int i = 0; i < 16; ++i) {
;       int n = nb + (i & 7) + 8 * hh + 16 * (i >> 3);
;       int dc = t - (16 * n + 31); int dd = dc < 0 ? 0 : (dc > 127 ? 127 : dc);
;       float z = dc < 0 ? NEGB : fmaf(s[i], C1, tabh[dd]);
;       s[i] = z; mloc = fmaxf(mloc, z);
.LBB0_1013:
	s_or_b64 exec, exec, s[14:15]
	v_add_u32_e32 v34, 0x90, v231
	v_cmp_lt_i32_e32 vcc, -1, v34
	v_mov_b32_e32 v0, 0xff800000
	v_mov_b32_e32 v221, 0xff800000
	s_and_saveexec_b64 s[14:15], vcc
	s_cbranch_execz .LBB0_1015
	v_min_u32_e32 v34, 0x7f, v34
	v_lshl_add_u32 v34, v34, 2, v250
	ds_read_b32 v221, v34
	s_waitcnt lgkmcnt(0)
	v_fmac_f32_e32 v221, 0x3e38aa3b, v48

; #define MFMA32(a, b, c) __builtin_amdgcn_mfma_f32_32x32x16_bf16((a), (b), (c), 0, 0, 0)
; DI float ex2(float x) { return __builtin_amdgcn_exp2f(x); }
; DI void nsa_phase(unsigned char* lds, KParamPtr P, int wv) {
;     ...
;         for (int wt = 0; wt < nwt; ++wt) {
;           const int s0 = s_lo + wt * 32;
;           bf16x8 vf[4];
; #pragma unroll
;           for (int st = 0; st < 2; ++st)
; #pragma unroll
;             for (int et = 0; et < 2; ++et) vf[st * 2 + et] = ldg8(vwT + vwo + (unsigned)(et * 32 * SEQ + wt * 32 + st * 16));
;           f32x16 s = zero16();
; #pragma unroll
;           for (int ks = 0; ks < 4; ++ks) s = MFMA32(kf[ks], qf[ks], s);
;           {
;             const int wn_ = wt + 1 < nwt ? wt + 1 : wt;
; #pragma unroll
;             for (int ks = 0; ks < 4; ++ks) kf[ks] = ldg8(proj + kwo + (unsigned)(wn_ * 32 * EIN + ks * 16));
;           }
;           float mloc = NEGB;
;           const bool full = (s0 + 31 <= t0) && (t0 + 31 - s0 < 512);
;           if (full && (t0 - (s0 + 31) >= 127)) {
;             const float bf = tabh[127];
; #pragma unroll
;             for (int i = 0; i < 16; ++i) { float z = fmaf(s[i], C1, bf); s[i] = z; mloc = fmaxf(mloc, z); }
;           } else {
; #pragma unroll
;             for (int i = 0; i < 16; ++i) {
;               int key = s0 + (i & 7) + 8 * hh + 16 * (i >> 3);
;               int dw = t - key; int dd = dw < 0 ? 0 : (dw > 127 ? 127 : dw);
;               float z = (dw >= 0 && dw < 512) ? fmaf(s[i], C1, tabh[dd]) : NEGB;
;               s[i] = z; mloc = fmaxf(mloc, z);
;             }
;           }
;           mloc = red_max32(mloc);
;           const float mn = fmaxf(m, mloc);
;           const float alpha = ex2(m - mn);
;           float ls = 0.f;
; #pragma unroll
;           for (int i = 0; i < 16; ++i) { float p = (s[i] > -1e29f) ? ex2(s[i] - mn) : 0.f; s[i] = p; ls += p; }
;           l = l * alpha + ls; m = mn;
; #pragma unroll
;           for (int et = 0; et < 2; ++et)
; #pragma unroll
;             for (int i = 0; i < 16; ++i) O[et][i] *= alpha;
; #pragma unroll
;           for (int st = 0; st < 2; ++st) {
;             bf16x8 pf = pack8(s, st);
; #pragma unroll
;             for (int et = 0; et < 2; ++et) O[et] = MFMA32(vf[st * 2 + et], pf, O[et]);
;           }
.LBB0_1037:
	s_or_b64 exec, exec, s[8:9]
	v_mov_b32_e32 v34, v0
	s_nop 1
	v_permlane32_swap_b32_e32 v0, v34
	v_max3_f32 v34, v219, v0, v34
	v_sub_f32_e32 v35, v198, v34
	v_exp_f32_e32 v36, v35
	v_sub_f32_e32 v0, v219, v34
	v_exp_f32_e32 v0, v0
	v_sub_f32_e32 v35, v199, v34
	v_exp_f32_e32 v37, v35
	v_pk_mul_f32 v[32:33], v[32:33], v[0:1] op_sel_hi:[1,0]
	v_pk_mul_f32 v[30:31], v[30:31], v[0:1] op_sel_hi:[1,0]
	v_sub_f32_e32 v35, v200, v34
	v_exp_f32_e32 v38, v35
	v_pk_mul_f32 v[28:29], v[28:29], v[0:1] op_sel_hi:[1,0]
	v_pk_mul_f32 v[26:27], v[26:27], v[0:1] op_sel_hi:[1,0]
	v_sub_f32_e32 v35, v201, v34
	v_exp_f32_e32 v39, v35
	v_pk_mul_f32 v[24:25], v[24:25], v[0:1] op_sel_hi:[1,0]
	v_pk_mul_f32 v[22:23], v[22:23], v[0:1] op_sel_hi:[1,0]
	v_sub_f32_e32 v35, v202, v34
	v_exp_f32_e32 v40, v35
	v_pk_mul_f32 v[20:21], v[20:21], v[0:1] op_sel_hi:[1,0]
	v_pk_mul_f32 v[18:19], v[18:19], v[0:1] op_sel_hi:[1,0]
	v_sub_f32_e32 v35, v203, v34
	v_exp_f32_e32 v41, v35
	v_pk_mul_f32 v[16:17], v[16:17], v[0:1] op_sel_hi:[1,0]
	v_pk_mul_f32 v[14:15], v[14:15], v[0:1] op_sel_hi:[1,0]
	v_sub_f32_e32 v35, v204, v34
	v_exp_f32_e32 v42, v35
	v_pk_mul_f32 v[12:13], v[12:13], v[0:1] op_sel_hi:[1,0]
	v_pk_mul_f32 v[10:11], v[10:11], v[0:1] op_sel_hi:[1,0]
	v_sub_f32_e32 v35, v205, v34
	v_exp_f32_e32 v43, v35
	v_pk_mul_f32 v[8:9], v[8:9], v[0:1] op_sel_hi:[1,0]
	v_pk_mul_f32 v[6:7], v[6:7], v[0:1] op_sel_hi:[1,0]
	v_sub_f32_e32 v35, v206, v34
	v_exp_f32_e32 v44, v35
	v_pk_mul_f32 v[4:5], v[4:5], v[0:1] op_sel_hi:[1,0]
	v_pk_mul_f32 v[2:3], v[2:3], v[0:1] op_sel_hi:[1,0]
	v_sub_f32_e32 v35, v207, v34
	v_exp_f32_e32 v45, v35
	v_subrev_u32_e32 v252, 32, v252
	v_add_u32_e32 v251, 32, v251
	v_sub_f32_e32 v35, v208, v34
	v_exp_f32_e32 v46, v35
	v_lshl_add_u64 v[196:197], v[196:197], 0, 64
	v_mov_b32_e32 v219, v34
	v_sub_f32_e32 v35, v209, v34
	v_exp_f32_e32 v47, v35
	s_nop 1
	v_sub_f32_e32 v35, v210, v34
	v_exp_f32_e32 v48, v35
	s_nop 1
	v_sub_f32_e32 v35, v211, v34
	v_exp_f32_e32 v49, v35
	s_nop 1
	v_sub_f32_e32 v35, v212, v34
	v_exp_f32_e32 v198, v35
	s_nop 1
	v_sub_f32_e32 v35, v213, v34
	v_exp_f32_e32 v199, v35
	s_nop 1
	v_add_f32_e32 v35, 0, v36
	v_add_f32_e32 v35, v37, v35
	v_add_f32_e32 v35, v38, v35
	v_add_f32_e32 v35, v39, v35
	v_cvt_pk_bf16_f32 v36, v36, v37
	v_cvt_pk_bf16_f32 v37, v38, v39
	v_cvt_pk_bf16_f32 v38, v40, v41
	v_cvt_pk_bf16_f32 v39, v42, v43
	v_add_f32_e32 v35, v40, v35
	v_add_f32_e32 v35, v41, v35
	s_waitcnt vmcnt(0) lgkmcnt(0)
	v_mfma_f32_32x32x16_bf16 v[18:33], v[158:161], v[36:39], v[18:33]
	v_add_f32_e32 v35, v42, v35
	v_add_f32_e32 v35, v43, v35
	v_add_f32_e32 v35, v44, v35
	v_add_f32_e32 v35, v45, v35
	v_add_f32_e32 v35, v46, v35
	v_add_f32_e32 v35, v47, v35
	v_add_f32_e32 v35, v48, v35
	v_mfma_f32_32x32x16_bf16 v[2:17], v[154:157], v[36:39], v[2:17]
	v_cvt_pk_bf16_f32 v36, v44, v45
	v_cvt_pk_bf16_f32 v37, v46, v47
	v_cvt_pk_bf16_f32 v38, v48, v49
	v_cvt_pk_bf16_f32 v39, v198, v199
	v_add_f32_e32 v35, v49, v35
	v_add_f32_e32 v35, v198, v35
	v_add_f32_e32 v35, v199, v35
	v_mfma_f32_32x32x16_bf16 v[18:33], v[150:153], v[36:39], v[18:33]
	v_fmac_f32_e32 v35, v253, v0
	v_cmp_eq_u32_e32 vcc, s17, v248
	s_or_b64 s[12:13], vcc, s[12:13]
	v_mov_b32_e32 v253, v35
	v_mfma_f32_32x32x16_bf16 v[2:17], v[146:149], v[36:39], v[2:17]
	s_andn2_b64 exec, exec, s[12:13]
	s_cbranch_execz .LBB0_1033
.LBB0_1038:
	v_mov_b32_e32 v231, 0xff800000
	s_waitcnt vmcnt(0) lgkmcnt(0)
	v_mfma_f32_32x32x16_bf16 v[34:49], v[142:145], v[114:117], 0
	s_mov_b32 s8, 0xfff7ffe0
	v_add_co_u32_e32 v142, vcc, s8, v196
	s_mov_b32 s8, 0xfff80000
	s_nop 0
	v_addc_co_u32_e32 v143, vcc, -1, v197, vcc
	v_add_co_u32_e32 v144, vcc, s3, v196
	v_mfma_f32_32x32x16_bf16 v[34:49], v[138:141], v[118:121], v[34:49]
	s_nop 0
	v_addc_co_u32_e32 v145, vcc, -1, v197, vcc
	v_add_co_u32_e32 v138, vcc, s8, v196
	s_mov_b32 s2, s17
	s_nop 0
	v_addc_co_u32_e32 v139, vcc, -1, v197, vcc
	v_mfma_f32_32x32x16_bf16 v[34:49], v[134:137], v[122:125], v[34:49]
	s_add_i32 s17, s17, 1
	v_mov_b32_e32 v0, s2
	v_mov_b32_e32 v134, s17
	v_cmp_lt_i32_e32 vcc, s17, v248
	s_mov_b32 s2, 0x13c00
	flat_load_dwordx4 v[158:161], v[142:143]
	flat_load_dwordx4 v[154:157], v[144:145]
	v_cndmask_b32_e32 v0, v0, v134, vcc
	v_mul_lo_u32 v0, v0, s2
	v_lshl_add_u64 v[198:199], v[0:1], 1, v[190:191]
	flat_load_dwordx4 v[150:153], v[138:139]
	flat_load_dwordx4 v[146:149], v[196:197]
	flat_load_dwordx4 v[142:145], v[198:199]
	s_nop 0
	flat_load_dwordx4 v[138:141], v[198:199] offset:32
	v_mfma_f32_32x32x16_bf16 v[34:49], v[130:133], v[126:129], v[34:49]
	flat_load_dwordx4 v[134:137], v[198:199] offset:64
	flat_load_dwordx4 v[130:133], v[198:199] offset:96
	v_cmp_gt_i32_e32 vcc, v251, v242
	v_cmp_lt_i32_e64 s[8:9], s1, v252
	v_subrev_u32_e32 v0, 62, v252
	s_or_b64 s[8:9], vcc, s[8:9]
	v_cmp_gt_i32_e32 vcc, s91, v0
	s_or_b64 s[8:9], s[8:9], vcc
	s_and_saveexec_b64 s[14:15], s[8:9]
	s_xor_b64 s[8:9], exec, s[14:15]
	s_cbranch_execz .LBB0_1072
	v_add_u32_e32 v0, v238, v252
	v_subrev_u32_e32 v200, 31, v0
	v_cmp_gt_u32_e32 vcc, s34, v200
	v_mov_b32_e32 v199, 0xff800000
	v_mov_b32_e32 v198, 0xff800000
	s_and_saveexec_b64 s[14:15], vcc
	s_cbranch_execz .LBB0_1041
	v_min_u32_e32 v198, 0x7f, v200
	v_lshl_add_u32 v198, v198, 2, v163
	ds_read_b32 v198, v198
	s_waitcnt lgkmcnt(0)
	v_fmac_f32_e32 v198, 0x3e38aa3b, v34

; DI void nsa_phase(unsigned char* lds, KParamPtr P, int wv) {
;     ...
; #pragma unroll
;             for (int i = 0; i < 16; ++i) {
;               int key = s0 + (i & 7) + 8 * hh + 16 * (i >> 3);
;               int dw = t - key; int dd = dw < 0 ? 0 : (dw > 127 ? 127 : dw);
;               float z = (dw >= 0 && dw < 512) ? fmaf(s[i], C1, tabh[dd]) : NEGB;
;               s[i] = z; mloc = fmaxf(mloc, z);
;             }
.LBB0_1043:
	s_or_b64 exec, exec, s[14:15]
	v_subrev_u32_e32 v34, 33, v0
	v_cmp_gt_u32_e32 vcc, s34, v34
	v_mov_b32_e32 v201, 0xff800000
	v_mov_b32_e32 v200, 0xff800000
	s_and_saveexec_b64 s[14:15], vcc
	s_cbranch_execz .LBB0_1045
	v_min_u32_e32 v34, 0x7f, v34
	v_lshl_add_u32 v34, v34, 2, v163
	ds_read_b32 v200, v34
	s_waitcnt lgkmcnt(0)
	v_fmac_f32_e32 v200, 0x3e38aa3b, v36

; DI void nsa_phase(unsigned char* lds, KParamPtr P, int wv) {
;     ...
; #pragma unroll
;             for (int i = 0; i < 16; ++i) {
;               int key = s0 + (i & 7) + 8 * hh + 16 * (i >> 3);
;               int dw = t - key; int dd = dw < 0 ? 0 : (dw > 127 ? 127 : dw);
;               float z = (dw >= 0 && dw < 512) ? fmaf(s[i], C1, tabh[dd]) : NEGB;
;               s[i] = z; mloc = fmaxf(mloc, z);
;             }
.LBB0_1047:
	s_or_b64 exec, exec, s[14:15]
	v_subrev_u32_e32 v34, 35, v0
	v_cmp_gt_u32_e32 vcc, s34, v34
	v_mov_b32_e32 v203, 0xff800000
	v_mov_b32_e32 v202, 0xff800000
	s_and_saveexec_b64 s[14:15], vcc
	s_cbranch_execz .LBB0_1049
	v_min_u32_e32 v34, 0x7f, v34
	v_lshl_add_u32 v34, v34, 2, v163
	ds_read_b32 v202, v34
	s_waitcnt lgkmcnt(0)
	v_fmac_f32_e32 v202, 0x3e38aa3b, v38

; DI void nsa_phase(unsigned char* lds, KParamPtr P, int wv) {
;     ...
; #pragma unroll
;             for (int i = 0; i < 16; ++i) {
;               int key = s0 + (i & 7) + 8 * hh + 16 * (i >> 3);
;               int dw = t - key; int dd = dw < 0 ? 0 : (dw > 127 ? 127 : dw);
;               float z = (dw >= 0 && dw < 512) ? fmaf(s[i], C1, tabh[dd]) : NEGB;
;               s[i] = z; mloc = fmaxf(mloc, z);
;             }
.LBB0_1051:
	s_or_b64 exec, exec, s[14:15]
	v_subrev_u32_e32 v34, 37, v0
	v_cmp_gt_u32_e32 vcc, s34, v34
	v_mov_b32_e32 v205, 0xff800000
	v_mov_b32_e32 v204, 0xff800000
	s_and_saveexec_b64 s[14:15], vcc
	s_cbranch_execz .LBB0_1053
	v_min_u32_e32 v34, 0x7f, v34
	v_lshl_add_u32 v34, v34, 2, v163
	ds_read_b32 v204, v34
	s_waitcnt lgkmcnt(0)
	v_fmac_f32_e32 v204, 0x3e38aa3b, v40

; DI void nsa_phase(unsigned char* lds, KParamPtr P, int wv) {
;     ...
; #pragma unroll
;             for (int i = 0; i < 16; ++i) {
;               int key = s0 + (i & 7) + 8 * hh + 16 * (i >> 3);
;               int dw = t - key; int dd = dw < 0 ? 0 : (dw > 127 ? 127 : dw);
;               float z = (dw >= 0 && dw < 512) ? fmaf(s[i], C1, tabh[dd]) : NEGB;
;               s[i] = z; mloc = fmaxf(mloc, z);
;             }
.LBB0_1055:
	s_or_b64 exec, exec, s[14:15]
	v_subrev_u32_e32 v34, 47, v0
	v_cmp_gt_u32_e32 vcc, s34, v34
	v_mov_b32_e32 v207, 0xff800000
	v_mov_b32_e32 v206, 0xff800000
	s_and_saveexec_b64 s[14:15], vcc
	s_cbranch_execz .LBB0_1057
	v_min_u32_e32 v34, 0x7f, v34
	v_lshl_add_u32 v34, v34, 2, v163
	ds_read_b32 v206, v34
	s_waitcnt lgkmcnt(0)
	v_fmac_f32_e32 v206, 0x3e38aa3b, v42

; DI void nsa_phase(unsigned char* lds, KParamPtr P, int wv) {
;     ...
; #pragma unroll
;             for (int i = 0; i < 16; ++i) {
;               int key = s0 + (i & 7) + 8 * hh + 16 * (i >> 3);
;               int dw = t - key; int dd = dw < 0 ? 0 : (dw > 127 ? 127 : dw);
;               float z = (dw >= 0 && dw < 512) ? fmaf(s[i], C1, tabh[dd]) : NEGB;
;               s[i] = z; mloc = fmaxf(mloc, z);
;             }
.LBB0_1059:
	s_or_b64 exec, exec, s[14:15]
	v_subrev_u32_e32 v34, 49, v0
	v_cmp_gt_u32_e32 vcc, s34, v34
	v_mov_b32_e32 v209, 0xff800000
	v_mov_b32_e32 v208, 0xff800000
	s_and_saveexec_b64 s[14:15], vcc
	s_cbranch_execz .LBB0_1061
	v_min_u32_e32 v34, 0x7f, v34
	v_lshl_add_u32 v34, v34, 2, v163
	ds_read_b32 v208, v34
	s_waitcnt lgkmcnt(0)
	v_fmac_f32_e32 v208, 0x3e38aa3b, v44

; DI void nsa_phase(unsigned char* lds, KParamPtr P, int wv) {
;     ...
; #pragma unroll
;             for (int i = 0; i < 16; ++i) {
;               int key = s0 + (i & 7) + 8 * hh + 16 * (i >> 3);
;               int dw = t - key; int dd = dw < 0 ? 0 : (dw > 127 ? 127 : dw);
;               float z = (dw >= 0 && dw < 512) ? fmaf(s[i], C1, tabh[dd]) : NEGB;
;               s[i] = z; mloc = fmaxf(mloc, z);
;             }
.LBB0_1063:
	s_or_b64 exec, exec, s[14:15]
	v_subrev_u32_e32 v34, 51, v0
	v_cmp_gt_u32_e32 vcc, s34, v34
	v_mov_b32_e32 v211, 0xff800000
	v_mov_b32_e32 v210, 0xff800000
	s_and_saveexec_b64 s[14:15], vcc
	s_cbranch_execz .LBB0_1065
	v_min_u32_e32 v34, 0x7f, v34
	v_lshl_add_u32 v34, v34, 2, v163
	ds_read_b32 v210, v34
	s_waitcnt lgkmcnt(0)
	v_fmac_f32_e32 v210, 0x3e38aa3b, v46

; DI void nsa_phase(unsigned char* lds, KParamPtr P, int wv) {
;     ...
; #pragma unroll
;             for (int i = 0; i < 16; ++i) {
;               int key = s0 + (i & 7) + 8 * hh + 16 * (i >> 3);
;               int dw = t - key; int dd = dw < 0 ? 0 : (dw > 127 ? 127 : dw);
;               float z = (dw >= 0 && dw < 512) ? fmaf(s[i], C1, tabh[dd]) : NEGB;
;               s[i] = z; mloc = fmaxf(mloc, z);
;             }
.LBB0_1067:
	s_or_b64 exec, exec, s[14:15]
	v_subrev_u32_e32 v34, 53, v0
	v_cmp_gt_u32_e32 vcc, s34, v34
	v_mov_b32_e32 v213, 0xff800000
	v_mov_b32_e32 v212, 0xff800000
	s_and_saveexec_b64 s[14:15], vcc
	s_cbranch_execz .LBB0_1069
	v_min_u32_e32 v34, 0x7f, v34
	v_lshl_add_u32 v34, v34, 2, v163
	ds_read_b32 v212, v34
	s_waitcnt lgkmcnt(0)
	v_fmac_f32_e32 v212, 0x3e38aa3b, v48

; #define MFMA16(a, b, c) __builtin_amdgcn_mfma_f32_16x16x32_bf16((a), (b), (c), 0, 0, 0)
; DI void nsa_phase(unsigned char* lds, KParamPtr P, int wv) {
;     ...
;         auto next_blk = [&]() -> int {
;           if (u0) { int bq = __builtin_ctz(u0); u0 &= u0 - 1u; return bq; }
;           if (u1) { int bq = __builtin_ctz(u1); u1 &= u1 - 1u; return 32 + bq; }
;           if (u2) { int bq = __builtin_ctz(u2); u2 &= u2 - 1u; return 64 + bq; }
;           if (u3) { int bq = __builtin_ctz(u3); u3 &= u3 - 1u; return 96 + bq; }
;           return -1;
;         };
;     ...
;         while (jb >= 0) {
;           const int base = jb * 64;
;           const unsigned mw = jb < 32 ? mym.x : (jb < 64 ? mym.y : (jb < 96 ? mym.z : mym.w));
;           const bool member = (mw >> (jb & 31)) & 1u;
;           f32x4 a[2][2];
; #pragma unroll
;           for (int hf = 0; hf < 2; ++hf)
; #pragma unroll
;             for (int tl = 0; tl < 2; ++tl) {
;               f32x4 acc = (f32x4){0.f, 0.f, 0.f, 0.f};
;               acc = MFMA16(kf[(hf * 2 + tl) * 2 + 0], qf[0], acc);
;               acc = MFMA16(kf[(hf * 2 + tl) * 2 + 1], qf[1], acc);
;               a[hf][tl] = acc;
;             }
;           const int jn = next_blk();
;           if (jn >= 0) load_k(jn);
.LBB0_1096:
	v_mov_b32_e32 v231, 0xff800000
	s_waitcnt vmcnt(0) lgkmcnt(0)
	v_mfma_f32_16x16x32_bf16 v[30:33], v[50:53], v[6:9], 0
	v_cmp_ne_u32_e32 vcc, 0, v121
	v_mfma_f32_16x16x32_bf16 v[42:45], v[54:57], v[10:13], v[30:33]
	v_mfma_f32_16x16x32_bf16 v[30:33], v[58:61], v[6:9], 0
	v_mfma_f32_16x16x32_bf16 v[38:41], v[62:65], v[10:13], v[30:33]
	v_mfma_f32_16x16x32_bf16 v[30:33], v[66:69], v[6:9], 0
	v_mfma_f32_16x16x32_bf16 v[34:37], v[70:73], v[10:13], v[30:33]
	v_mfma_f32_16x16x32_bf16 v[30:33], v[74:77], v[6:9], 0
	v_mfma_f32_16x16x32_bf16 v[30:33], v[78:81], v[10:13], v[30:33]
	s_and_saveexec_b64 s[12:13], vcc
	s_xor_b64 s[12:13], exec, s[12:13]
	v_add_u32_e32 v0, -1, v121
	v_ffbl_b32_e32 v134, v121
	v_and_b32_e32 v121, v0, v121
	s_andn2_saveexec_b64 s[12:13], s[12:13]
	s_cbranch_execz .LBB0_1108
	v_cmp_ne_u32_e32 vcc, 0, v131
	s_and_saveexec_b64 s[14:15], vcc
	s_xor_b64 s[14:15], exec, s[14:15]
	v_ffbl_b32_e32 v0, v131
	v_add_u32_e32 v121, -1, v131
	v_and_b32_e32 v131, v121, v131
	v_or_b32_e32 v134, 32, v0
	s_andn2_saveexec_b64 s[14:15], s[14:15]
	s_cbranch_execz .LBB0_1107
	v_cmp_ne_u32_e32 vcc, 0, v130
	s_and_saveexec_b64 s[16:17], vcc
	s_xor_b64 s[16:17], exec, s[16:17]
	v_ffbl_b32_e32 v0, v130
	v_add_u32_e32 v121, -1, v130
	v_and_b32_e32 v130, v121, v130
	v_or_b32_e32 v134, 64, v0
	s_andn2_saveexec_b64 s[16:17], s[16:17]
	v_ffbl_b32_e32 v0, v129
	v_or_b32_e32 v0, 0x60, v0
	v_subrev_co_u32_e32 v121, vcc, 1, v129
	v_and_b32_e32 v129, v121, v129
	s_nop 0
	v_cndmask_b32_e64 v134, v0, -1, vcc
	v_mov_b32_e32 v130, 0
	s_or_b64 exec, exec, s[16:17]
	v_mov_b32_e32 v131, 0

; DI void nsa_phase(unsigned char* lds, KParamPtr P, int wv) {
;     ...
;           const int base = jb * 64;
;           const unsigned mw = jb < 32 ? mym.x : (jb < 64 ? mym.y : (jb < 96 ? mym.z : mym.w));
;           const bool member = (mw >> (jb & 31)) & 1u;
;     ...
; #pragma unroll
;             for (int hf = 0; hf < 2; ++hf)
; #pragma unroll
;               for (int tl = 0; tl < 2; ++tl)
; #pragma unroll
;                 for (int j = 0; j < 4; ++j) {
;                   int key = base + hf * 32 + 8 * q4 + 4 * tl + j;
;                   int dist = tq - key; int dd = dist < 0 ? 0 : (dist > 127 ? 127 : dist);
;                   float z = (dist < 0 || !member) ? NEGB : fmaf(a[hf][tl][j], C1, tabc[dd]);
;                   a[hf][tl][j] = z; mloc = fmaxf(mloc, z);
.LBB0_1110:
	s_or_b64 exec, exec, s[16:17]
	s_movk_i32 s2, 0x60
	v_cmp_gt_u32_e32 vcc, s2, v136
	v_lshlrev_b32_e32 v152, 6, v136
	s_nop 0
	v_cndmask_b32_e32 v0, v5, v4, vcc
	v_cmp_gt_u32_e32 vcc, 64, v136
	s_nop 1
	v_cndmask_b32_e32 v0, v0, v3, vcc
	v_cmp_gt_u32_e32 vcc, 32, v136
	s_nop 1
	v_cndmask_b32_e32 v0, v0, v2, vcc
	v_lshrrev_b32_e32 v0, v136, v0
	v_and_b32_e32 v0, 1, v0
	v_cmp_eq_u32_e32 vcc, 1, v0
	v_sub_u32_e32 v0, v132, v152
	v_cmp_gt_i32_e64 s[16:17], s91, v0
	s_and_saveexec_b64 s[36:37], s[16:17]
	s_xor_b64 s[36:37], exec, s[36:37]
	s_cbranch_execz .LBB0_1144
	v_or_b32_e32 v151, v152, v170
	v_sub_u32_e32 v136, v120, v151
	v_cmp_lt_i32_e64 s[16:17], -1, v136
	s_and_b64 s[42:43], s[16:17], vcc
	v_mov_b32_e32 v0, 0xff800000
	v_mov_b32_e32 v137, 0xff800000
	s_and_saveexec_b64 s[16:17], s[42:43]
	s_cbranch_execz .LBB0_1113
	v_min_u32_e32 v136, 0x7f, v136
	v_lshl_add_u32 v136, v136, 2, v122
	ds_read_b32 v137, v136
	s_waitcnt lgkmcnt(0)
	v_fmac_f32_e32 v137, 0x3e38aa3b, v42

; DI void nsa_phase(unsigned char* lds, KParamPtr P, int wv) {
;     ...
;                 for (int j = 0; j < 4; ++j) {
;                   int key = base + hf * 32 + 8 * q4 + 4 * tl + j;
;                   int dist = tq - key; int dd = dist < 0 ? 0 : (dist > 127 ? 127 : dist);
;                   float z = (dist < 0 || !member) ? NEGB : fmaf(a[hf][tl][j], C1, tabc[dd]);
;                   a[hf][tl][j] = z; mloc = fmaxf(mloc, z);
.LBB0_1115:
	s_or_b64 exec, exec, s[16:17]
	v_or_b32_e32 v42, 2, v151
	v_sub_u32_e32 v42, v120, v42
	v_cmp_lt_i32_e64 s[16:17], -1, v42
	s_and_b64 s[42:43], s[16:17], vcc
	v_mov_b32_e32 v136, 0xff800000
	v_mov_b32_e32 v138, 0xff800000
	s_and_saveexec_b64 s[16:17], s[42:43]
	s_cbranch_execz .LBB0_1117
	v_min_u32_e32 v42, 0x7f, v42
	v_lshl_add_u32 v42, v42, 2, v122
	ds_read_b32 v138, v42
	s_waitcnt lgkmcnt(0)
	v_fmac_f32_e32 v138, 0x3e38aa3b, v44

; DI void nsa_phase(unsigned char* lds, KParamPtr P, int wv) {
;     ...
;                 for (int j = 0; j < 4; ++j) {
;                   int key = base + hf * 32 + 8 * q4 + 4 * tl + j;
;                   int dist = tq - key; int dd = dist < 0 ? 0 : (dist > 127 ? 127 : dist);
;                   float z = (dist < 0 || !member) ? NEGB : fmaf(a[hf][tl][j], C1, tabc[dd]);
;                   a[hf][tl][j] = z; mloc = fmaxf(mloc, z);
.LBB0_1119:
	s_or_b64 exec, exec, s[16:17]
	v_or_b32_e32 v42, 4, v151
	v_sub_u32_e32 v42, v120, v42
	v_cmp_lt_i32_e64 s[16:17], -1, v42
	s_and_b64 s[42:43], s[16:17], vcc
	v_mov_b32_e32 v139, 0xff800000
	v_mov_b32_e32 v141, 0xff800000
	s_and_saveexec_b64 s[16:17], s[42:43]
	s_cbranch_execz .LBB0_1121
	v_min_u32_e32 v42, 0x7f, v42
	v_lshl_add_u32 v42, v42, 2, v122
	ds_read_b32 v141, v42
	s_waitcnt lgkmcnt(0)
	v_fmac_f32_e32 v141, 0x3e38aa3b, v38

; DI void nsa_phase(unsigned char* lds, KParamPtr P, int wv) {
;     ...
;                 for (int j = 0; j < 4; ++j) {
;                   int key = base + hf * 32 + 8 * q4 + 4 * tl + j;
;                   int dist = tq - key; int dd = dist < 0 ? 0 : (dist > 127 ? 127 : dist);
;                   float z = (dist < 0 || !member) ? NEGB : fmaf(a[hf][tl][j], C1, tabc[dd]);
;                   a[hf][tl][j] = z; mloc = fmaxf(mloc, z);
.LBB0_1123:
	s_or_b64 exec, exec, s[16:17]
	v_or_b32_e32 v38, 6, v151
	v_sub_u32_e32 v38, v120, v38
	v_cmp_lt_i32_e64 s[16:17], -1, v38
	s_and_b64 s[42:43], s[16:17], vcc
	v_mov_b32_e32 v140, 0xff800000
	v_mov_b32_e32 v142, 0xff800000
	s_and_saveexec_b64 s[16:17], s[42:43]
	s_cbranch_execz .LBB0_1125
	v_min_u32_e32 v38, 0x7f, v38
	v_lshl_add_u32 v38, v38, 2, v122
	ds_read_b32 v142, v38
	s_waitcnt lgkmcnt(0)
	v_fmac_f32_e32 v142, 0x3e38aa3b, v40

; DI void nsa_phase(unsigned char* lds, KParamPtr P, int wv) {
;     ...
;                 for (int j = 0; j < 4; ++j) {
;                   int key = base + hf * 32 + 8 * q4 + 4 * tl + j;
;                   int dist = tq - key; int dd = dist < 0 ? 0 : (dist > 127 ? 127 : dist);
;                   float z = (dist < 0 || !member) ? NEGB : fmaf(a[hf][tl][j], C1, tabc[dd]);
;                   a[hf][tl][j] = z; mloc = fmaxf(mloc, z);
.LBB0_1127:
	s_or_b64 exec, exec, s[16:17]
	v_or_b32_e32 v38, 32, v151
	v_sub_u32_e32 v38, v120, v38
	v_cmp_lt_i32_e64 s[16:17], -1, v38
	s_and_b64 s[42:43], s[16:17], vcc
	v_mov_b32_e32 v143, 0xff800000
	v_mov_b32_e32 v145, 0xff800000
	s_and_saveexec_b64 s[16:17], s[42:43]
	s_cbranch_execz .LBB0_1129
	v_min_u32_e32 v38, 0x7f, v38
	v_lshl_add_u32 v38, v38, 2, v122
	ds_read_b32 v145, v38
	s_waitcnt lgkmcnt(0)
	v_fmac_f32_e32 v145, 0x3e38aa3b, v34

; DI void nsa_phase(unsigned char* lds, KParamPtr P, int wv) {
;     ...
;                 for (int j = 0; j < 4; ++j) {
;                   int key = base + hf * 32 + 8 * q4 + 4 * tl + j;
;                   int dist = tq - key; int dd = dist < 0 ? 0 : (dist > 127 ? 127 : dist);
;                   float z = (dist < 0 || !member) ? NEGB : fmaf(a[hf][tl][j], C1, tabc[dd]);
;                   a[hf][tl][j] = z; mloc = fmaxf(mloc, z);
.LBB0_1131:
	s_or_b64 exec, exec, s[16:17]
	v_or_b32_e32 v34, 34, v151
	v_sub_u32_e32 v34, v120, v34
	v_cmp_lt_i32_e64 s[16:17], -1, v34
	s_and_b64 s[42:43], s[16:17], vcc
	v_mov_b32_e32 v144, 0xff800000
	v_mov_b32_e32 v146, 0xff800000
	s_and_saveexec_b64 s[16:17], s[42:43]
	s_cbranch_execz .LBB0_1133
	v_min_u32_e32 v34, 0x7f, v34
	v_lshl_add_u32 v34, v34, 2, v122
	ds_read_b32 v146, v34
	s_waitcnt lgkmcnt(0)
	v_fmac_f32_e32 v146, 0x3e38aa3b, v36

; DI void nsa_phase(unsigned char* lds, KParamPtr P, int wv) {
;     ...
;                 for (int j = 0; j < 4; ++j) {
;                   int key = base + hf * 32 + 8 * q4 + 4 * tl + j;
;                   int dist = tq - key; int dd = dist < 0 ? 0 : (dist > 127 ? 127 : dist);
;                   float z = (dist < 0 || !member) ? NEGB : fmaf(a[hf][tl][j], C1, tabc[dd]);
;                   a[hf][tl][j] = z; mloc = fmaxf(mloc, z);
.LBB0_1135:
	s_or_b64 exec, exec, s[16:17]
	v_or_b32_e32 v34, 36, v151
	v_sub_u32_e32 v34, v120, v34
	v_cmp_lt_i32_e64 s[16:17], -1, v34
	s_and_b64 s[42:43], s[16:17], vcc
	v_mov_b32_e32 v147, 0xff800000
	v_mov_b32_e32 v148, 0xff800000
	s_and_saveexec_b64 s[16:17], s[42:43]
	s_cbranch_execz .LBB0_1137
	v_min_u32_e32 v34, 0x7f, v34
	v_lshl_add_u32 v34, v34, 2, v122
	ds_read_b32 v148, v34
	s_waitcnt lgkmcnt(0)
	v_fmac_f32_e32 v148, 0x3e38aa3b, v30

; DI void nsa_phase(unsigned char* lds, KParamPtr P, int wv) {
;     ...
;                 for (int j = 0; j < 4; ++j) {
;                   int key = base + hf * 32 + 8 * q4 + 4 * tl + j;
;                   int dist = tq - key; int dd = dist < 0 ? 0 : (dist > 127 ? 127 : dist);
;                   float z = (dist < 0 || !member) ? NEGB : fmaf(a[hf][tl][j], C1, tabc[dd]);
;                   a[hf][tl][j] = z; mloc = fmaxf(mloc, z);
.LBB0_1139:
	s_or_b64 exec, exec, s[16:17]
	v_or_b32_e32 v30, 38, v151
	v_sub_u32_e32 v30, v120, v30
	v_cmp_lt_i32_e64 s[16:17], -1, v30
	s_and_b64 s[42:43], s[16:17], vcc
	v_mov_b32_e32 v149, 0xff800000
	v_mov_b32_e32 v150, 0xff800000
	s_and_saveexec_b64 s[16:17], s[42:43]
	s_cbranch_execz .LBB0_1141
	v_min_u32_e32 v30, 0x7f, v30
	v_lshl_add_u32 v30, v30, 2, v122
	ds_read_b32 v150, v30
	s_waitcnt lgkmcnt(0)
	v_fmac_f32_e32 v150, 0x3e38aa3b, v32

; #define MFMA16(a, b, c) __builtin_amdgcn_mfma_f32_16x16x32_bf16((a), (b), (c), 0, 0, 0)
; DI unsigned pk2(float a, float b) { f32x2 v = {a, b}; bfx2 r = __builtin_convertvector(v, bfx2); return __builtin_bit_cast(unsigned, r); }
; DI float ex2(float x) { return __builtin_amdgcn_exp2f(x); }
; DI void nsa_phase(unsigned char* lds, KParamPtr P, int wv) {
;     ...
;           if (tmin - (base + 63) >= 127) {
;             const float bf = tabc[127];
; #pragma unroll
;             for (int hf = 0; hf < 2; ++hf)
; #pragma unroll
;               for (int tl = 0; tl < 2; ++tl)
; #pragma unroll
;                 for (int j = 0; j < 4; ++j) { float z = member ? fmaf(a[hf][tl][j], C1, bf) : NEGB; a[hf][tl][j] = z; mloc = fmaxf(mloc, z); }
;           } else {
; #pragma unroll
;             for (int hf = 0; hf < 2; ++hf)
; #pragma unroll
;               for (int tl = 0; tl < 2; ++tl)
; #pragma unroll
;                 for (int j = 0; j < 4; ++j) {
;                   int key = base + hf * 32 + 8 * q4 + 4 * tl + j;
;                   int dist = tq - key; int dd = dist < 0 ? 0 : (dist > 127 ? 127 : dist);
;                   float z = (dist < 0 || !member) ? NEGB : fmaf(a[hf][tl][j], C1, tabc[dd]);
;                   a[hf][tl][j] = z; mloc = fmaxf(mloc, z);
;                 }
;           }
;           mloc = red_max16(mloc);
;           mloc = red_max32(mloc);
;           const float mn = fmaxf(m, mloc);
;           const float alpha = ex2(m - mn);
;           float ls = 0.f;
; #pragma unroll
;           for (int hf = 0; hf < 2; ++hf)
; #pragma unroll
;             for (int tl = 0; tl < 2; ++tl)
; #pragma unroll
;               for (int j = 0; j < 4; ++j) { float p = (a[hf][tl][j] > -1e29f) ? ex2(a[hf][tl][j] - mn) : 0.f; a[hf][tl][j] = p; ls += p; }
;           l = l * alpha + ls; m = mn;
; #pragma unroll
;           for (int e = 0; e < 4; ++e) O[e] *= alpha;
; #pragma unroll
;           for (int hf = 0; hf < 2; ++hf) {
;             u32x4 u; u.x = pk2(a[hf][0][0], a[hf][0][1]); u.y = pk2(a[hf][0][2], a[hf][0][3]); u.z = pk2(a[hf][1][0], a[hf][1][1]); u.w = pk2(a[hf][1][2], a[hf][1][3]);
;             const bf16x8 pf = __builtin_bit_cast(bf16x8, u);
; #pragma unroll
;             for (int e = 0; e < 4; ++e) O[e] = MFMA16(vf[hf * 4 + e], pf, O[e]);
;           }
;           if (jn >= 0) load_v(jn);
.LBB0_1144:
	s_andn2_saveexec_b64 s[16:17], s[36:37]
	s_cbranch_execz .LBB0_1146
	ds_read_b32 v149, v122 offset:508
	s_waitcnt lgkmcnt(0)
	v_fmamk_f32 v0, v42, 0x3e38aa3b, v149
	v_fmamk_f32 v42, v43, 0x3e38aa3b, v149
	v_fmamk_f32 v43, v44, 0x3e38aa3b, v149
	v_cndmask_b32_e32 v137, v231, v0, vcc
	v_cndmask_b32_e32 v0, v231, v42, vcc
	v_cndmask_b32_e32 v138, v231, v43, vcc
	v_fmamk_f32 v43, v45, 0x3e38aa3b, v149
	v_fmamk_f32 v38, v38, 0x3e38aa3b, v149
	v_max3_f32 v42, v137, s52, v0
	v_cndmask_b32_e32 v136, v231, v43, vcc
	v_cndmask_b32_e32 v141, v231, v38, vcc
	v_fmamk_f32 v38, v39, 0x3e38aa3b, v149
	v_fmamk_f32 v39, v40, 0x3e38aa3b, v149
	v_max3_f32 v42, v42, v138, v136
	v_cndmask_b32_e32 v139, v231, v38, vcc
	v_cndmask_b32_e32 v142, v231, v39, vcc
	v_fmamk_f32 v39, v41, 0x3e38aa3b, v149
	v_fmamk_f32 v34, v34, 0x3e38aa3b, v149
	v_max3_f32 v38, v42, v141, v139
	v_cndmask_b32_e32 v140, v231, v39, vcc
	v_cndmask_b32_e32 v145, v231, v34, vcc
	v_fmamk_f32 v34, v35, 0x3e38aa3b, v149
	v_fmamk_f32 v35, v36, 0x3e38aa3b, v149
	v_max3_f32 v38, v38, v142, v140
	v_cndmask_b32_e32 v143, v231, v34, vcc
	v_cndmask_b32_e32 v146, v231, v35, vcc
	v_fmamk_f32 v35, v37, 0x3e38aa3b, v149
	v_fmamk_f32 v30, v30, 0x3e38aa3b, v149
	v_max3_f32 v34, v38, v145, v143
	v_cndmask_b32_e32 v144, v231, v35, vcc
	v_cndmask_b32_e32 v148, v231, v30, vcc
	v_fmamk_f32 v30, v31, 0x3e38aa3b, v149
	v_max3_f32 v34, v34, v146, v144
	v_cndmask_b32_e32 v147, v231, v30, vcc
	v_fmamk_f32 v31, v32, 0x3e38aa3b, v149
	v_fmac_f32_e32 v149, 0x3e38aa3b, v33
	v_max3_f32 v30, v34, v148, v147
	v_cndmask_b32_e32 v150, v231, v31, vcc
	v_cndmask_b32_e32 v149, v231, v149, vcc
	v_max3_f32 v151, v30, v150, v149
.LBB0_1146:
	s_or_b64 exec, exec, s[16:17]
	v_mov_b32_e32 v30, v151
	s_nop 1
	v_permlane16_swap_b32_e32 v151, v30
	v_max_f32_e32 v30, v30, v30
	v_max_f32_e32 v31, v151, v151
	v_max_f32_e32 v30, v31, v30
	v_mov_b32_e32 v31, v30
	s_nop 1
	v_permlane32_swap_b32_e32 v30, v31
	v_max3_f32 v31, v135, v30, v31
	v_sub_f32_e32 v32, v137, v31
	v_exp_f32_e32 v32, v32
	v_sub_f32_e32 v30, v135, v31
	v_exp_f32_e32 v30, v30
	v_sub_f32_e32 v0, v0, v31
	v_exp_f32_e32 v33, v0
	v_pk_mul_f32 v[28:29], v[28:29], v[30:31] op_sel_hi:[1,0]
	v_pk_mul_f32 v[26:27], v[26:27], v[30:31] op_sel_hi:[1,0]
	v_pk_mul_f32 v[24:25], v[24:25], v[30:31] op_sel_hi:[1,0]
	v_sub_f32_e32 v0, v138, v31
	v_exp_f32_e32 v34, v0
	v_pk_mul_f32 v[22:23], v[22:23], v[30:31] op_sel_hi:[1,0]
	v_pk_mul_f32 v[20:21], v[20:21], v[30:31] op_sel_hi:[1,0]
	v_sub_f32_e32 v0, v136, v31
	v_exp_f32_e32 v35, v0
	v_pk_mul_f32 v[18:19], v[18:19], v[30:31] op_sel_hi:[1,0]
	v_pk_mul_f32 v[16:17], v[16:17], v[30:31] op_sel_hi:[1,0]
	v_sub_f32_e32 v0, v141, v31
	v_exp_f32_e32 v36, v0
	v_pk_mul_f32 v[14:15], v[14:15], v[30:31] op_sel_hi:[1,0]
	v_cvt_pk_bf16_f32 v138, v32, v33
	v_sub_f32_e32 v0, v139, v31
	v_exp_f32_e32 v37, v0
	v_cvt_pk_bf16_f32 v139, v34, v35
	s_nop 0
	v_sub_f32_e32 v0, v142, v31
	v_exp_f32_e32 v38, v0
	s_nop 1
	v_sub_f32_e32 v0, v140, v31
	v_exp_f32_e32 v39, v0
	v_cvt_pk_bf16_f32 v140, v36, v37
	s_nop 0
	v_sub_f32_e32 v0, v145, v31
	v_exp_f32_e32 v40, v0
	v_cvt_pk_bf16_f32 v141, v38, v39
	s_nop 0
	v_sub_f32_e32 v0, v143, v31
	v_exp_f32_e32 v41, v0
	v_mfma_f32_16x16x32_bf16 v[26:29], v[82:85], v[138:141], v[26:29]
	s_nop 0
	v_sub_f32_e32 v0, v146, v31
	v_exp_f32_e32 v42, v0
	v_mfma_f32_16x16x32_bf16 v[22:25], v[94:97], v[138:141], v[22:25]
	s_nop 0
	v_sub_f32_e32 v0, v144, v31
	v_exp_f32_e32 v43, v0
	v_mfma_f32_16x16x32_bf16 v[18:21], v[102:105], v[138:141], v[18:21]
	s_nop 0
	v_sub_f32_e32 v0, v148, v31
	v_exp_f32_e32 v44, v0
	v_mfma_f32_16x16x32_bf16 v[14:17], v[110:113], v[138:141], v[14:17]
	v_cvt_pk_bf16_f32 v138, v40, v41
	v_sub_f32_e32 v0, v147, v31
	v_exp_f32_e32 v45, v0
	v_cvt_pk_bf16_f32 v139, v42, v43
	s_nop 0
	v_sub_f32_e32 v0, v150, v31
	v_exp_f32_e32 v135, v0
	v_cvt_pk_bf16_f32 v140, v44, v45
	s_nop 0
	v_sub_f32_e32 v0, v149, v31
	v_exp_f32_e32 v136, v0
	s_nop 1
	v_cvt_pk_bf16_f32 v141, v135, v136
	s_nop 1
	v_mfma_f32_16x16x32_bf16 v[26:29], v[86:89], v[138:141], v[26:29]
	v_mfma_f32_16x16x32_bf16 v[22:25], v[90:93], v[138:141], v[22:25]
	v_mfma_f32_16x16x32_bf16 v[18:21], v[98:101], v[138:141], v[18:21]
	v_mfma_f32_16x16x32_bf16 v[14:17], v[106:109], v[138:141], v[14:17]
	s_and_saveexec_b64 s[16:17], s[14:15]
	s_cbranch_execz .LBB0_1095
	v_lshlrev_b32_e32 v0, 6, v134
	v_add_lshl_u32 v0, v0, v124, 1
	v_lshl_add_u64 v[86:87], s[22:23], 0, v[0:1]
	v_add_co_u32_e32 v90, vcc, 0x40000, v86
	s_nop 1
	v_addc_co_u32_e32 v91, vcc, 0, v87, vcc
	v_add_co_u32_e32 v98, vcc, 0x80000, v86
	s_nop 1
	v_addc_co_u32_e32 v99, vcc, 0, v87, vcc
	v_add_co_u32_e32 v106, vcc, 0xc0000, v86
	s_nop 1
	v_addc_co_u32_e32 v107, vcc, 0, v87, vcc
	flat_load_dwordx4 v[82:85], v[86:87]
	s_nop 0
	flat_load_dwordx4 v[86:89], v[86:87] offset:64
	s_nop 0
	flat_load_dwordx4 v[94:97], v[90:91]
	s_nop 0
	flat_load_dwordx4 v[90:93], v[90:91] offset:64
	s_nop 0
	flat_load_dwordx4 v[102:105], v[98:99]
	s_nop 0
	flat_load_dwordx4 v[98:101], v[98:99] offset:64
	s_nop 0
	flat_load_dwordx4 v[110:113], v[106:107]
	s_nop 0
	flat_load_dwordx4 v[106:109], v[106:107] offset:64
	s_branch .LBB0_1095
